# GA loop: loop-invariant LDS and global address math hoisted out of the tile loop (per-copy fixed stage offsets, scalar tile offsets)
# speedup vs baseline: 1.0048x; 1.0048x over previous
.LBB0_1273:
	s_andn2_b64 vcc, exec, s[0:1]
	s_cbranch_vccnz .LBB0_1287
	s_lshl_b32 s0, s22, 1
	s_addk_i32 s0, 0xfeb0
	v_mov_b32_e32 v20, v201
	v_add_u32_e32 v8, s0, v149
	v_lshlrev_b32_e32 v0, 6, v8
	v_lshrrev_b32_e32 v6, 1, v20
	v_and_b32_e32 v2, 32, v6
	s_movk_i32 s0, 0xfc0
	v_ashrrev_i32_e32 v106, 7, v8
	v_bfe_u32 v5, v8, 6, 1
	v_and_or_b32 v0, v0, s0, v2
	v_mov_b64_e32 v[2:3], s[42:43]
	s_mov_b32 s0, 0x220000
	v_mad_i64_i32 v[2:3], s[0:1], v106, s0, v[2:3]
	v_lshlrev_b32_e32 v4, 7, v5
	v_and_or_b32 v110, v6, 64, v4
	v_mov_b64_e32 v[6:7], s[58:59]
	s_mov_b32 s0, 0x110000
	v_add_u32_e32 v108, 0x100, v0
	v_lshlrev_b32_e32 v0, 1, v110
	v_mad_i64_i32 v[6:7], s[0:1], v106, s0, v[6:7]
	v_and_b32_e32 v107, 15, v20
	v_bfe_u32 v21, v20, 4, 2
	v_lshl_add_u64 v[2:3], v[2:3], 0, v[0:1]
	v_lshlrev_b32_e32 v0, 6, v5
	v_mov_b32_e32 v5, v1
	s_movk_i32 s0, 0xff80
	v_lshl_add_u64 v[4:5], v[6:7], 0, v[4:5]
	v_and_or_b32 v6, v8, s0, v0
	v_or_b32_e32 v7, v108, v107
	v_lshlrev_b32_e32 v0, 4, v21
	v_lshl_add_u64 v[2:3], v[2:3], 0, v[0:1]
	v_lshlrev_b32_e32 v0, 9, v7
	v_lshl_add_u64 v[2:3], v[2:3], 0, v[0:1]
	s_movk_i32 s0, 0x2000
	global_load_dwordx4 v[46:49], v[2:3], off
	global_load_dwordx4 v[42:45], v[2:3], off offset:64
	v_add_co_u32_e32 v2, vcc, s0, v2
	v_and_b32_e32 v22, 7, v20
	s_nop 0
	v_addc_co_u32_e32 v3, vcc, 0, v3, vcc
	global_load_dwordx4 v[50:53], v[2:3], off
	global_load_dwordx4 v[54:57], v[2:3], off offset:64
	v_mov_b64_e32 v[2:3], s[44:45]
	v_bfe_u32 v126, v20, 3, 5
	v_lshlrev_b32_e32 v114, 4, v22
	v_mov_b32_e32 v115, v1
	v_mad_i64_i32 v[2:3], s[0:1], v6, s85, v[2:3]
	v_lshl_add_u64 v[116:117], v[4:5], 0, v[114:115]
	v_lshlrev_b32_e32 v0, 8, v126
	v_or_b32_e32 v23, 32, v126
	v_lshl_add_u64 v[18:19], v[2:3], 0, v[114:115]
	v_lshl_add_u64 v[2:3], v[116:117], 0, v[0:1]
	v_lshlrev_b32_e32 v0, 8, v23
	v_mad_u64_u32 v[6:7], s[0:1], v126, s85, v[18:19]
	v_lshl_add_u64 v[10:11], v[116:117], 0, v[0:1]
	v_mad_u64_u32 v[14:15], s[0:1], v23, s85, v[18:19]
	v_mov_b32 v122, 0xc2800000
	global_load_dwordx4 v[2:5], v[2:3], off
	s_nop 0
	global_load_dwordx4 v[6:9], v[6:7], off
	s_nop 0
	global_load_dwordx4 v[10:13], v[10:11], off
	s_nop 0
	global_load_dwordx4 v[14:17], v[14:15], off
	v_lshrrev_b32_e32 v26, 3, v20
	v_lshrrev_b32_e32 v25, 4, v20
	v_xor_b32_e32 v20, v26, v20
	v_lshlrev_b32_e32 v20, 4, v20
	v_and_b32_e32 v132, 0x70, v20
	v_lshlrev_b32_e32 v112, 3, v21
	v_lshlrev_b32_e32 v127, 7, v126
	v_bitop3_b32 v21, v21, v22, 4 bitop3:0x36
	v_add_u32_e32 v20, v150, v132
	v_and_b32_e32 v24, 64, v208
	v_mul_u32_u24_e32 v128, 0x90, v126
	v_lshlrev_b32_e32 v131, 7, v23
	v_lshlrev_b32_e32 v129, 4, v21
	v_add_u32_e32 v21, v20, v127
	v_xor_b32_e32 v0, 16, v208
	v_bitop3_b32 v25, v25, v22, 3 bitop3:0x6c
	v_add3_u32 v22, v150, v114, v128
	v_add_u32_e32 v20, v20, v131
	v_lshlrev_b32_e32 v130, 4, v25
	v_mov_b32_e32 v38, 0
	s_mov_b32 s0, 0
	v_lshlrev_b32_e32 v115, 7, v107
	v_mov_b32_e32 v123, v122
	v_mov_b32_e32 v165, 0
	v_mov_b32_e32 v152, 0x42800000
	v_mov_b32_e32 v153, v152
	v_mov_b32_e32 v154, v152
	v_mov_b32_e32 v155, v152
	v_mov_b32_e32 v156, v152
	v_mov_b32_e32 v157, v152
	v_mov_b32_e32 v158, v152
	v_mov_b32_e32 v159, v152
	v_mul_u32_u24_e32 v109, 0x90, v107
	v_mov_b32_e32 v39, v38
	v_mov_b32_e32 v40, v38
	v_mov_b32_e32 v41, v38
	v_mov_b32_e32 v34, v38
	v_mov_b32_e32 v35, v38
	v_mov_b32_e32 v36, v38
	v_mov_b32_e32 v37, v38
	s_waitcnt vmcnt(0) lgkmcnt(0)
	ds_write_b128 v21, v[2:5]
	ds_write_b128 v22, v[6:9] offset:8192
	ds_write_b128 v20, v[10:13]
	ds_write_b128 v22, v[14:17] offset:12800
	v_add_u32_e32 v2, 64, v24
	v_cmp_lt_i32_e32 vcc, v0, v2
	v_mov_b32_e32 v3, v1
	s_waitcnt lgkmcnt(0)
	v_cndmask_b32_e32 v0, v208, v0, vcc
	v_lshlrev_b32_e32 v111, 2, v0
	v_xor_b32_e32 v0, 32, v208
	v_cmp_lt_i32_e32 vcc, v0, v2
	v_mov_b32_e32 v2, v1
	s_barrier
	v_cndmask_b32_e32 v0, v208, v0, vcc
	v_lshlrev_b32_e32 v113, 2, v0
	v_mul_u32_u24_e32 v0, 0x1100, v126
	v_lshlrev_b32_e32 v0, 1, v0
	v_lshl_add_u64 v[120:121], v[18:19], 0, v[0:1]
	v_mov_b32_e32 v0, v1
	v_mov_b64_e32 v[20:21], v[2:3]
	v_mov_b64_e32 v[24:25], v[2:3]
	v_mov_b64_e32 v[28:29], v[2:3]
	v_mov_b64_e32 v[32:33], v[2:3]
	v_mov_b64_e32 v[12:13], v[2:3]
	v_mov_b64_e32 v[16:17], v[2:3]
	v_mov_b64_e32 v[8:9], v[2:3]
	v_mov_b64_e32 v[18:19], v[0:1]
	v_mov_b64_e32 v[22:23], v[0:1]
	v_mov_b64_e32 v[26:27], v[0:1]
	v_mov_b64_e32 v[30:31], v[0:1]
	v_mov_b64_e32 v[10:11], v[0:1]
	v_mov_b64_e32 v[14:15], v[0:1]
	v_mov_b64_e32 v[6:7], v[0:1]
	v_mov_b64_e32 v[4:5], v[2:3]
	v_mov_b64_e32 v[2:3], v[0:1]
	v_add_u32_e32 v170, v150, v115
	v_add_u32_e32 v171, v170, v129
	v_add_u32_e32 v170, v170, v130
	v_add3_u32 v172, v150, v109, v112
	v_add_u32_e32 v173, 0x2800, v172
	v_add_u32_e32 v174, 0x6400, v172
	v_add_u32_e32 v175, 0x6c00, v172
	v_add_u32_e32 v176, 0x3000, v172
	v_add_u32_e32 v177, 0x3800, v172
	v_add_u32_e32 v178, 0x7400, v172
	v_add_u32_e32 v179, 0x7c00, v172
	v_add_u32_e32 v172, 0x2000, v172
	v_add_u32_e32 v180, v150, v132
	v_add_u32_e32 v181, v180, v131
	v_add_u32_e32 v180, v180, v127
	v_add3_u32 v182, v150, v114, v128
	v_lshlrev_b32_e32 v164, 8, v126
	v_lshl_add_u64 v[184:185], v[116:117], 0, v[164:165]
	s_mov_b64 s[2:3], 0x2000
	v_lshl_add_u64 v[186:187], v[184:185], 0, s[2:3]
	s_mov_b64 s[2:3], 0x44000
	v_lshl_add_u64 v[188:189], v[120:121], 0, s[2:3]
	s_mov_b32 s1, 1
	v_lshl_or_b32 v68, s1, 6, v126
	v_lshlrev_b32_e32 v0, 8, v68
	s_lshl_b32 s56, s1, 7
	v_lshl_add_u64 v[58:59], v[116:117], 0, v[0:1]
	v_lshl_add_u64 v[66:67], v[120:121], 0, s[56:57]
	v_or_b32_e32 v0, 32, v68
	s_mov_b32 s1, 0x44000
	v_lshlrev_b64 v[68:69], 8, v[0:1]
	v_add_co_u32_e32 v70, vcc, s1, v66
	v_lshl_add_u64 v[68:69], v[116:117], 0, v[68:69]
	s_nop 0
	v_addc_co_u32_e32 v71, vcc, 0, v67, vcc
	global_load_dwordx4 v[58:61], v[58:59], off
	s_nop 0
	global_load_dwordx4 v[62:65], v[66:67], off
	s_nop 0
	global_load_dwordx4 v[66:69], v[68:69], off
	s_nop 0
	global_load_dwordx4 v[70:73], v[70:71], off
.LBB0_1275:
	s_add_i32 s0, s0, 1
	s_add_i32 s1, s0, 1
	s_min_u32 s1, s1, 0x43
	ds_read_b128 v[74:77], v170
	ds_read_b128 v[82:85], v170 offset:2048
	ds_read_b128 v[86:89], v171
	ds_read_b128 v[98:101], v171 offset:2048
	s_lshl_b32 s2, s1, 14
	s_lshl_b32 s56, s1, 7
	v_lshl_add_u64 v[228:229], v[184:185], 0, s[2:3]
	v_lshl_add_u64 v[236:237], v[120:121], 0, s[56:57]
	v_lshl_add_u64 v[238:239], v[186:187], 0, s[2:3]
	v_lshl_add_u64 v[240:241], v[188:189], 0, s[56:57]
	global_load_dwordx4 v[228:231], v[228:229], off
	s_nop 0
	global_load_dwordx4 v[232:235], v[236:237], off
	s_nop 0
	global_load_dwordx4 v[236:239], v[238:239], off
	s_nop 0
	global_load_dwordx4 v[240:243], v[240:241], off
	s_setprio 1
	s_waitcnt lgkmcnt(0)
	v_mfma_f32_16x16x32_bf16 v[78:81], v[74:77], v[46:49], v[152:155]
	v_mfma_f32_16x16x32_bf16 v[74:77], v[74:77], v[50:53], v[156:159]
	v_mfma_f32_16x16x32_bf16 v[94:97], v[86:89], v[42:45], v[78:81]
	v_mfma_f32_16x16x32_bf16 v[78:81], v[86:89], v[54:57], v[74:77]
	v_mfma_f32_16x16x32_bf16 v[74:77], v[82:85], v[46:49], v[152:155]
	v_mfma_f32_16x16x32_bf16 v[90:93], v[98:101], v[42:45], v[74:77]
	v_mfma_f32_16x16x32_bf16 v[74:77], v[82:85], v[50:53], v[156:159]
	ds_read_b128 v[82:85], v170 offset:4096
	ds_read_b128 v[134:137], v170 offset:6144
	v_mfma_f32_16x16x32_bf16 v[74:77], v[98:101], v[54:57], v[74:77]
	ds_read_b128 v[98:101], v171 offset:4096
	ds_read_b128 v[138:141], v171 offset:6144
	s_waitcnt lgkmcnt(0)
	ds_read2_b64 v[212:215], v172 offset1:4
	ds_read2_b64 v[216:219], v172 offset0:8 offset1:12
	ds_read2_b64 v[244:247], v173 offset0:32 offset1:36
	ds_read2_b64 v[248:251], v173 offset0:40 offset1:44
	v_mfma_f32_16x16x32_bf16 v[86:89], v[82:85], v[46:49], v[152:155]
	v_mfma_f32_16x16x32_bf16 v[82:85], v[82:85], v[50:53], v[156:159]
	v_mfma_f32_16x16x32_bf16 v[102:105], v[98:101], v[42:45], v[86:89]
	v_mfma_f32_16x16x32_bf16 v[86:89], v[98:101], v[54:57], v[82:85]
	v_mfma_f32_16x16x32_bf16 v[82:85], v[134:137], v[46:49], v[152:155]
	v_mfma_f32_16x16x32_bf16 v[98:101], v[138:141], v[42:45], v[82:85]
	v_mfma_f32_16x16x32_bf16 v[82:85], v[134:137], v[50:53], v[156:159]
	v_mfma_f32_16x16x32_bf16 v[82:85], v[138:141], v[54:57], v[82:85]
	s_setprio 0
	v_max3_f32 v118, v94, v95, v96
	v_max3_f32 v119, v97, v90, v91
	v_max3_f32 v118, v118, v92, v93
	v_max3_f32 v118, v118, v119, v102
	v_max3_f32 v119, v103, v104, v105
	v_max3_f32 v118, v118, v119, v98
	v_max3_f32 v119, v99, v100, v101
	v_max_f32_e32 v118, v118, v119
	v_mov_b32_e32 v119, v118
	s_nop 1
	v_permlane16_swap_b32_e32 v119, v118
	v_max_f32_e32 v118, v118, v119
	v_mov_b32_e32 v119, v118
	s_nop 1
	v_permlane32_swap_b32_e32 v119, v118
	v_max_f32_e32 v118, v118, v119
	v_cmp_lt_f32_e32 vcc, 0x41000000, v118
	s_cbranch_vccz .LBB0_1277
	v_max_f32_e32 v119, 0, v118
	v_add_f32_e32 v124, v122, v119
	v_exp_f32_e64 v118, -v119
	v_mov_b32_e32 v125, v123
	v_mov_b32_e32 v122, v124
	v_xor_b32_e32 v152, 0x80000000, v124
	v_mov_b32_e32 v153, v152
	v_mov_b32_e32 v154, v152
	v_mov_b32_e32 v155, v152
	v_sub_f32_e32 v94, v94, v119
	v_sub_f32_e32 v95, v95, v119
	v_sub_f32_e32 v96, v96, v119
	v_sub_f32_e32 v97, v97, v119
	v_sub_f32_e32 v90, v90, v119
	v_sub_f32_e32 v91, v91, v119
	v_sub_f32_e32 v92, v92, v119
	v_sub_f32_e32 v93, v93, v119
	v_sub_f32_e32 v102, v102, v119
	v_sub_f32_e32 v103, v103, v119
	v_sub_f32_e32 v104, v104, v119
	v_sub_f32_e32 v105, v105, v119
	v_sub_f32_e32 v98, v98, v119
	v_sub_f32_e32 v99, v99, v119
	v_sub_f32_e32 v100, v100, v119
	v_sub_f32_e32 v101, v101, v119
	v_pk_mul_f32 v[38:39], v[38:39], v[118:119] op_sel_hi:[1,0]
	v_pk_mul_f32 v[40:41], v[40:41], v[118:119] op_sel_hi:[1,0]
	v_pk_mul_f32 v[32:33], v[32:33], v[118:119] op_sel_hi:[1,0]
	v_pk_mul_f32 v[30:31], v[30:31], v[118:119] op_sel_hi:[1,0]
	v_pk_mul_f32 v[24:25], v[24:25], v[118:119] op_sel_hi:[1,0]
	v_pk_mul_f32 v[22:23], v[22:23], v[118:119] op_sel_hi:[1,0]
	v_pk_mul_f32 v[12:13], v[12:13], v[118:119] op_sel_hi:[1,0]
	v_pk_mul_f32 v[10:11], v[10:11], v[118:119] op_sel_hi:[1,0]
	v_pk_mul_f32 v[8:9], v[8:9], v[118:119] op_sel_hi:[1,0]
	v_pk_mul_f32 v[6:7], v[6:7], v[118:119] op_sel_hi:[1,0]
	s_branch .LBB0_1278

.LBB0_1280:
	v_exp_f32_e32 v134, v74
	v_exp_f32_e32 v135, v75
	v_exp_f32_e32 v136, v76
	v_exp_f32_e32 v137, v77
	v_exp_f32_e32 v138, v86
	v_exp_f32_e32 v139, v87
	v_exp_f32_e32 v140, v88
	v_exp_f32_e32 v141, v89
	v_exp_f32_e32 v122, v78
	v_exp_f32_e32 v142, v82
	v_exp_f32_e32 v123, v79
	v_exp_f32_e32 v143, v83
	s_mov_b32 s38, s36
	s_mov_b32 s39, s36
	v_mov_b64_e32 v[118:119], v[124:125]
	v_exp_f32_e32 v124, v80
	v_exp_f32_e32 v144, v84
	v_exp_f32_e32 v125, v85
	s_mov_b32 s37, s36
	v_mov_b64_e32 v[84:85], s[38:39]
	v_exp_f32_e32 v94, v94
	v_exp_f32_e32 v95, v95
	v_exp_f32_e32 v96, v96
	v_exp_f32_e32 v97, v97
	v_exp_f32_e32 v90, v90
	v_exp_f32_e32 v91, v91
	v_exp_f32_e32 v92, v92
	v_exp_f32_e32 v93, v93
	v_exp_f32_e32 v133, v81
	v_mov_b64_e32 v[82:83], s[36:37]
	v_exp_f32_e32 v102, v102
	v_exp_f32_e32 v103, v103
	v_exp_f32_e32 v104, v104
	v_exp_f32_e32 v105, v105
	v_exp_f32_e32 v98, v98
	v_exp_f32_e32 v99, v99
	v_exp_f32_e32 v100, v100
	v_exp_f32_e32 v101, v101
	v_cvt_pk_bf16_f32 v74, v94, v95
	v_cvt_pk_bf16_f32 v75, v96, v97
	v_cvt_pk_bf16_f32 v76, v90, v91
	v_cvt_pk_bf16_f32 v77, v92, v93
	v_cvt_pk_bf16_f32 v86, v122, v123
	v_cvt_pk_bf16_f32 v87, v124, v133
	v_cvt_pk_bf16_f32 v88, v134, v135
	v_cvt_pk_bf16_f32 v89, v136, v137
	v_mfma_f32_16x16x32_bf16 v[38:41], v[82:85], v[74:77], v[38:41]
	v_cvt_pk_bf16_f32 v78, v102, v103
	v_cvt_pk_bf16_f32 v79, v104, v105
	v_cvt_pk_bf16_f32 v80, v98, v99
	v_mfma_f32_16x16x32_bf16 v[34:37], v[82:85], v[86:89], v[34:37]
	v_cvt_pk_bf16_f32 v81, v100, v101
	v_cvt_pk_bf16_f32 v90, v138, v139
	v_cvt_pk_bf16_f32 v91, v140, v141
	v_cvt_pk_bf16_f32 v92, v142, v143
	v_cvt_pk_bf16_f32 v93, v144, v125
	v_mfma_f32_16x16x32_bf16 v[38:41], v[82:85], v[78:81], v[38:41]
	s_nop 0
	v_mfma_f32_16x16x32_bf16 v[34:37], v[82:85], v[90:93], v[34:37]
	s_setprio 1
	s_waitcnt vmcnt(4)
	ds_write_b128 v180, v[58:61] offset:17408
	ds_write_b128 v182, v[62:65] offset:25600
	ds_write_b128 v181, v[66:69] offset:17408
	ds_write_b128 v182, v[70:73] offset:30208
	ds_read2_b64 v[94:97], v176 offset0:64 offset1:68
	ds_read2_b64 v[98:101], v176 offset0:72 offset1:76
	ds_read2_b64 v[102:105], v177 offset0:96 offset1:100
	ds_read2_b64 v[134:137], v177 offset0:104 offset1:108
	s_waitcnt lgkmcnt(4)
	v_mfma_f32_16x16x32_bf16 v[30:33], v[212:215], v[74:77], v[30:33]
	v_mfma_f32_16x16x32_bf16 v[26:29], v[212:215], v[86:89], v[26:29]
	v_mfma_f32_16x16x32_bf16 v[22:25], v[244:247], v[74:77], v[22:25]
	v_mfma_f32_16x16x32_bf16 v[18:21], v[244:247], v[86:89], v[18:21]
	v_mfma_f32_16x16x32_bf16 v[30:33], v[216:219], v[78:81], v[30:33]
	v_mfma_f32_16x16x32_bf16 v[26:29], v[216:219], v[90:93], v[26:29]
	v_mfma_f32_16x16x32_bf16 v[22:25], v[248:251], v[78:81], v[22:25]
	v_mfma_f32_16x16x32_bf16 v[18:21], v[248:251], v[90:93], v[18:21]
	s_waitcnt lgkmcnt(0)
	v_mfma_f32_16x16x32_bf16 v[10:13], v[94:97], v[74:77], v[10:13]
	v_mfma_f32_16x16x32_bf16 v[14:17], v[94:97], v[86:89], v[14:17]
	v_mfma_f32_16x16x32_bf16 v[6:9], v[102:105], v[74:77], v[6:9]
	v_mfma_f32_16x16x32_bf16 v[2:5], v[102:105], v[86:89], v[2:5]
	v_mfma_f32_16x16x32_bf16 v[10:13], v[98:101], v[78:81], v[10:13]
	v_mfma_f32_16x16x32_bf16 v[14:17], v[98:101], v[90:93], v[14:17]
	v_mfma_f32_16x16x32_bf16 v[6:9], v[134:137], v[78:81], v[6:9]
	v_mfma_f32_16x16x32_bf16 v[2:5], v[134:137], v[90:93], v[2:5]
	s_setprio 0
	s_cmpk_lg_i32 s0, 0x43
	s_waitcnt lgkmcnt(0)
	s_barrier
	s_cbranch_scc0 .LBB0_1282
	v_mov_b64_e32 v[122:123], v[118:119]
	s_branch .Lga_odd
.Lga_odd:
	s_add_i32 s0, s0, 1
	s_add_i32 s1, s0, 1
	s_min_u32 s1, s1, 0x43
	ds_read_b128 v[74:77], v170 offset:17408
	ds_read_b128 v[82:85], v170 offset:19456
	ds_read_b128 v[86:89], v171 offset:17408
	ds_read_b128 v[98:101], v171 offset:19456
	s_lshl_b32 s2, s1, 14
	s_lshl_b32 s56, s1, 7
	v_lshl_add_u64 v[58:59], v[184:185], 0, s[2:3]
	v_lshl_add_u64 v[66:67], v[120:121], 0, s[56:57]
	v_lshl_add_u64 v[68:69], v[186:187], 0, s[2:3]
	v_lshl_add_u64 v[70:71], v[188:189], 0, s[56:57]
	global_load_dwordx4 v[58:61], v[58:59], off
	s_nop 0
	global_load_dwordx4 v[62:65], v[66:67], off
	s_nop 0
	global_load_dwordx4 v[66:69], v[68:69], off
	s_nop 0
	global_load_dwordx4 v[70:73], v[70:71], off
	s_setprio 1
	s_waitcnt lgkmcnt(0)
	v_mfma_f32_16x16x32_bf16 v[78:81], v[74:77], v[46:49], v[152:155]
	v_mfma_f32_16x16x32_bf16 v[74:77], v[74:77], v[50:53], v[156:159]
	v_mfma_f32_16x16x32_bf16 v[94:97], v[86:89], v[42:45], v[78:81]
	v_mfma_f32_16x16x32_bf16 v[78:81], v[86:89], v[54:57], v[74:77]
	v_mfma_f32_16x16x32_bf16 v[74:77], v[82:85], v[46:49], v[152:155]
	v_mfma_f32_16x16x32_bf16 v[90:93], v[98:101], v[42:45], v[74:77]
	v_mfma_f32_16x16x32_bf16 v[74:77], v[82:85], v[50:53], v[156:159]
	ds_read_b128 v[82:85], v170 offset:21504
	ds_read_b128 v[134:137], v170 offset:23552
	v_mfma_f32_16x16x32_bf16 v[74:77], v[98:101], v[54:57], v[74:77]
	ds_read_b128 v[98:101], v171 offset:21504
	ds_read_b128 v[138:141], v171 offset:23552
	s_waitcnt lgkmcnt(0)
	ds_read2_b64 v[212:215], v174 offset1:4
	ds_read2_b64 v[216:219], v174 offset0:8 offset1:12
	ds_read2_b64 v[244:247], v175 offset0:32 offset1:36
	ds_read2_b64 v[248:251], v175 offset0:40 offset1:44
	v_mfma_f32_16x16x32_bf16 v[86:89], v[82:85], v[46:49], v[152:155]
	v_mfma_f32_16x16x32_bf16 v[82:85], v[82:85], v[50:53], v[156:159]
	v_mfma_f32_16x16x32_bf16 v[102:105], v[98:101], v[42:45], v[86:89]
	v_mfma_f32_16x16x32_bf16 v[86:89], v[98:101], v[54:57], v[82:85]
	v_mfma_f32_16x16x32_bf16 v[82:85], v[134:137], v[46:49], v[152:155]
	v_mfma_f32_16x16x32_bf16 v[98:101], v[138:141], v[42:45], v[82:85]
	v_mfma_f32_16x16x32_bf16 v[82:85], v[134:137], v[50:53], v[156:159]
	v_mfma_f32_16x16x32_bf16 v[82:85], v[138:141], v[54:57], v[82:85]
	s_setprio 0
	v_max3_f32 v118, v94, v95, v96
	v_max3_f32 v119, v97, v90, v91
	v_max3_f32 v118, v118, v92, v93
	v_max3_f32 v118, v118, v119, v102
	v_max3_f32 v119, v103, v104, v105
	v_max3_f32 v118, v118, v119, v98
	v_max3_f32 v119, v99, v100, v101
	v_max_f32_e32 v118, v118, v119
	v_mov_b32_e32 v119, v118
	s_nop 1
	v_permlane16_swap_b32_e32 v119, v118
	v_max_f32_e32 v118, v118, v119
	v_mov_b32_e32 v119, v118
	s_nop 1
	v_permlane32_swap_b32_e32 v119, v118
	v_max_f32_e32 v118, v118, v119
	v_cmp_lt_f32_e32 vcc, 0x41000000, v118
	s_cbranch_vccz .Lga_o_1277
	v_max_f32_e32 v119, 0, v118
	v_add_f32_e32 v124, v122, v119
	v_exp_f32_e64 v118, -v119
	v_mov_b32_e32 v125, v123
	v_mov_b32_e32 v122, v124
	v_xor_b32_e32 v152, 0x80000000, v124
	v_mov_b32_e32 v153, v152
	v_mov_b32_e32 v154, v152
	v_mov_b32_e32 v155, v152
	v_sub_f32_e32 v94, v94, v119
	v_sub_f32_e32 v95, v95, v119
	v_sub_f32_e32 v96, v96, v119
	v_sub_f32_e32 v97, v97, v119
	v_sub_f32_e32 v90, v90, v119
	v_sub_f32_e32 v91, v91, v119
	v_sub_f32_e32 v92, v92, v119
	v_sub_f32_e32 v93, v93, v119
	v_sub_f32_e32 v102, v102, v119
	v_sub_f32_e32 v103, v103, v119
	v_sub_f32_e32 v104, v104, v119
	v_sub_f32_e32 v105, v105, v119
	v_sub_f32_e32 v98, v98, v119
	v_sub_f32_e32 v99, v99, v119
	v_sub_f32_e32 v100, v100, v119
	v_sub_f32_e32 v101, v101, v119
	v_pk_mul_f32 v[38:39], v[38:39], v[118:119] op_sel_hi:[1,0]
	v_pk_mul_f32 v[40:41], v[40:41], v[118:119] op_sel_hi:[1,0]
	v_pk_mul_f32 v[32:33], v[32:33], v[118:119] op_sel_hi:[1,0]
	v_pk_mul_f32 v[30:31], v[30:31], v[118:119] op_sel_hi:[1,0]
	v_pk_mul_f32 v[24:25], v[24:25], v[118:119] op_sel_hi:[1,0]
	v_pk_mul_f32 v[22:23], v[22:23], v[118:119] op_sel_hi:[1,0]
	v_pk_mul_f32 v[12:13], v[12:13], v[118:119] op_sel_hi:[1,0]
	v_pk_mul_f32 v[10:11], v[10:11], v[118:119] op_sel_hi:[1,0]
	v_pk_mul_f32 v[8:9], v[8:9], v[118:119] op_sel_hi:[1,0]
	v_pk_mul_f32 v[6:7], v[6:7], v[118:119] op_sel_hi:[1,0]
	s_branch .Lga_o_1278

.Lga_o_1280:
	v_exp_f32_e32 v134, v74
	v_exp_f32_e32 v135, v75
	v_exp_f32_e32 v136, v76
	v_exp_f32_e32 v137, v77
	v_exp_f32_e32 v138, v86
	v_exp_f32_e32 v139, v87
	v_exp_f32_e32 v140, v88
	v_exp_f32_e32 v141, v89
	v_exp_f32_e32 v122, v78
	v_exp_f32_e32 v142, v82
	v_exp_f32_e32 v123, v79
	v_exp_f32_e32 v143, v83
	s_mov_b32 s38, s36
	s_mov_b32 s39, s36
	v_mov_b64_e32 v[118:119], v[124:125]
	v_exp_f32_e32 v124, v80
	v_exp_f32_e32 v144, v84
	v_exp_f32_e32 v125, v85
	s_mov_b32 s37, s36
	v_mov_b64_e32 v[84:85], s[38:39]
	v_exp_f32_e32 v94, v94
	v_exp_f32_e32 v95, v95
	v_exp_f32_e32 v96, v96
	v_exp_f32_e32 v97, v97
	v_exp_f32_e32 v90, v90
	v_exp_f32_e32 v91, v91
	v_exp_f32_e32 v92, v92
	v_exp_f32_e32 v93, v93
	v_exp_f32_e32 v133, v81
	v_mov_b64_e32 v[82:83], s[36:37]
	v_exp_f32_e32 v102, v102
	v_exp_f32_e32 v103, v103
	v_exp_f32_e32 v104, v104
	v_exp_f32_e32 v105, v105
	v_exp_f32_e32 v98, v98
	v_exp_f32_e32 v99, v99
	v_exp_f32_e32 v100, v100
	v_exp_f32_e32 v101, v101
	v_cvt_pk_bf16_f32 v74, v94, v95
	v_cvt_pk_bf16_f32 v75, v96, v97
	v_cvt_pk_bf16_f32 v76, v90, v91
	v_cvt_pk_bf16_f32 v77, v92, v93
	v_cvt_pk_bf16_f32 v86, v122, v123
	v_cvt_pk_bf16_f32 v87, v124, v133
	v_cvt_pk_bf16_f32 v88, v134, v135
	v_cvt_pk_bf16_f32 v89, v136, v137
	v_mfma_f32_16x16x32_bf16 v[38:41], v[82:85], v[74:77], v[38:41]
	v_cvt_pk_bf16_f32 v78, v102, v103
	v_cvt_pk_bf16_f32 v79, v104, v105
	v_cvt_pk_bf16_f32 v80, v98, v99
	v_mfma_f32_16x16x32_bf16 v[34:37], v[82:85], v[86:89], v[34:37]
	v_cvt_pk_bf16_f32 v81, v100, v101
	v_cvt_pk_bf16_f32 v90, v138, v139
	v_cvt_pk_bf16_f32 v91, v140, v141
	v_cvt_pk_bf16_f32 v92, v142, v143
	v_cvt_pk_bf16_f32 v93, v144, v125
	v_mfma_f32_16x16x32_bf16 v[38:41], v[82:85], v[78:81], v[38:41]
	s_nop 0
	v_mfma_f32_16x16x32_bf16 v[34:37], v[82:85], v[90:93], v[34:37]
	s_setprio 1
	s_waitcnt vmcnt(4)
	ds_write_b128 v180, v[228:231]
	ds_write_b128 v182, v[232:235] offset:8192
	ds_write_b128 v181, v[236:239]
	ds_write_b128 v182, v[240:243] offset:12800
	ds_read2_b64 v[94:97], v178 offset0:64 offset1:68
	ds_read2_b64 v[98:101], v178 offset0:72 offset1:76
	ds_read2_b64 v[102:105], v179 offset0:96 offset1:100
	ds_read2_b64 v[134:137], v179 offset0:104 offset1:108
	s_waitcnt lgkmcnt(4)
	v_mfma_f32_16x16x32_bf16 v[30:33], v[212:215], v[74:77], v[30:33]
	v_mfma_f32_16x16x32_bf16 v[26:29], v[212:215], v[86:89], v[26:29]
	v_mfma_f32_16x16x32_bf16 v[22:25], v[244:247], v[74:77], v[22:25]
	v_mfma_f32_16x16x32_bf16 v[18:21], v[244:247], v[86:89], v[18:21]
	v_mfma_f32_16x16x32_bf16 v[30:33], v[216:219], v[78:81], v[30:33]
	v_mfma_f32_16x16x32_bf16 v[26:29], v[216:219], v[90:93], v[26:29]
	v_mfma_f32_16x16x32_bf16 v[22:25], v[248:251], v[78:81], v[22:25]
	v_mfma_f32_16x16x32_bf16 v[18:21], v[248:251], v[90:93], v[18:21]
	s_waitcnt lgkmcnt(0)
	v_mfma_f32_16x16x32_bf16 v[10:13], v[94:97], v[74:77], v[10:13]
	v_mfma_f32_16x16x32_bf16 v[14:17], v[94:97], v[86:89], v[14:17]
	v_mfma_f32_16x16x32_bf16 v[6:9], v[102:105], v[74:77], v[6:9]
	v_mfma_f32_16x16x32_bf16 v[2:5], v[102:105], v[86:89], v[2:5]
	v_mfma_f32_16x16x32_bf16 v[10:13], v[98:101], v[78:81], v[10:13]
	v_mfma_f32_16x16x32_bf16 v[14:17], v[98:101], v[90:93], v[14:17]
	v_mfma_f32_16x16x32_bf16 v[6:9], v[134:137], v[78:81], v[6:9]
	v_mfma_f32_16x16x32_bf16 v[2:5], v[134:137], v[90:93], v[2:5]
	s_setprio 0
	s_cmpk_lg_i32 s0, 0x43
	s_waitcnt lgkmcnt(0)
	s_barrier
	s_cbranch_scc0 .LBB0_1282
	v_mov_b64_e32 v[122:123], v[118:119]
	s_branch .LBB0_1275
